# GEMM job preambles: vmcnt waits that only covered the previous epilogue's stores removed (first-tile loads issue without waiting for store acks)
# baseline (speedup 1.0000x reference)
.LBB0_140:
	s_abs_i32 s2, s0
	v_readlane_b32 s3, v254, 36
	s_mul_hi_u32 s3, s2, s3
	s_mul_i32 s4, s3, s6
	s_sub_i32 s2, s2, s4
	s_ashr_i32 s1, s0, 31
	s_add_i32 s4, s3, 1
	s_sub_i32 s5, s2, s6
	s_cmp_ge_u32 s2, s6
	s_cselect_b32 s3, s4, s3
	s_cselect_b32 s2, s5, s2
	s_add_i32 s4, s3, 1
	s_cmp_ge_u32 s2, s6
	s_cselect_b32 s2, s4, s3
	s_xor_b32 s2, s2, s1
	s_sub_i32 s2, s2, s1
	s_lshr_b32 s1, s1, 30
	s_add_i32 s1, s0, s1
	s_ashr_i32 s3, s1, 2
	s_abs_i32 s3, s3
	v_readlane_b32 s5, v254, 38
	s_mul_hi_u32 s5, s3, s5
	v_readlane_b32 s6, v254, 37
	s_mul_i32 s5, s5, s6
	s_and_b32 s4, s1, 0xfffffc
	s_sub_i32 s3, s3, s5
	s_sub_i32 s4, s0, s4
	s_ashr_i32 s1, s1, 31
	s_sub_i32 s5, s3, s6
	s_cmp_ge_u32 s3, s6
	s_cselect_b32 s3, s5, s3
	s_sub_i32 s5, s3, s6
	s_cmp_ge_u32 s3, s6
	s_cselect_b32 s3, s5, s3
	s_xor_b32 s3, s3, s1
	s_sub_i32 s1, s3, s1
	v_readlane_b32 s3, v254, 32
	s_add_i32 s3, s3, s1
	s_lshl_b32 s1, s2, 10
	s_lshl_b32 s2, s4, 8
	v_mov_b32_e32 v136, v208
	v_readlane_b32 s4, v253, 28
	s_add_i32 s1, s1, s2
	v_readlane_b32 s5, v253, 29
	v_ashrrev_i32_e32 v4, 2, v136
	s_lshl_b32 s2, s3, 7
	v_add_u32_e32 v2, s1, v4
	v_mov_b64_e32 v[0:1], s[4:5]
	s_movk_i32 s3, 0x1600
	v_mad_i64_i32 v[0:1], s[4:5], v2, s3, v[0:1]
	v_lshlrev_b32_e32 v5, 4, v136
	v_readlane_b32 s4, v253, 61
	s_addk_i32 s2, 0x3000
	v_and_b32_e32 v192, 48, v5
	v_readlane_b32 s5, v253, 62
	v_lshl_add_u64 v[68:69], v[0:1], 0, v[192:193]
	v_add_u32_e32 v2, s2, v4
	v_mov_b64_e32 v[0:1], s[4:5]
	v_mad_i64_i32 v[0:1], s[4:5], v2, s3, v[0:1]
	s_mov_b32 s3, 0x58000
	v_add_co_u32_e32 v8, vcc, s3, v68
	s_mov_b32 s4, 0xb0000
	s_nop 0
	v_addc_co_u32_e32 v9, vcc, 0, v69, vcc
	v_add_co_u32_e32 v12, vcc, s4, v68
	s_mov_b32 s4, 0x108000
	s_nop 0
	v_addc_co_u32_e32 v13, vcc, 0, v69, vcc
	v_bfe_u32 v6, v136, 5, 1
	v_lshrrev_b32_e32 v7, 2, v136
	v_bfe_u32 v10, v136, 2, 2
	v_add_co_u32_e32 v16, vcc, s4, v68
	v_lshlrev_b32_e32 v11, 1, v136
	v_bitop3_b32 v7, v6, v7, 3 bitop3:0x78
	v_bitop3_b32 v6, v6, v10, 2 bitop3:0x36
	v_ashrrev_i32_e32 v10, 1, v136
	v_lshl_add_u64 v[70:71], v[0:1], 0, v[192:193]
	v_addc_co_u32_e32 v17, vcc, 0, v69, vcc
	v_and_b32_e32 v137, 31, v136
	v_and_b32_e32 v138, 0x80, v11
	v_and_b32_e32 v139, 0xffffffc0, v10
	v_add_co_u32_e32 v24, vcc, s3, v70
	v_or_b32_e32 v11, v138, v137
	v_or_b32_e32 v10, v139, v137
	global_load_dwordx4 v[0:3], v[68:69], off
	global_load_dwordx4 v[28:31], v[8:9], off
	global_load_dwordx4 v[32:35], v[12:13], off
	global_load_dwordx4 v[36:39], v[16:17], off
	global_load_dwordx4 v[40:43], v[70:71], off
	v_addc_co_u32_e32 v25, vcc, 0, v71, vcc
	v_bitop3_b32 v5, v5, 48, v136 bitop3:0x48
	v_lshlrev_b32_e32 v11, 6, v11
	v_lshlrev_b32_e32 v7, 4, v7
	v_lshlrev_b32_e32 v6, 4, v6
	v_lshl_add_u32 v10, v10, 6, v214
	global_load_dwordx4 v[44:47], v[24:25], off
	v_or_b32_e32 v80, v11, v7
	v_or_b32_e32 v81, v11, v6
	v_or_b32_e32 v82, v10, v7
	v_or_b32_e32 v83, v10, v6
	v_lshl_or_b32 v84, v4, 6, v5
	global_load_dwordx4 v[4:7], v[68:69], off offset:64
	s_nop 0
	global_load_dwordx4 v[8:11], v[8:9], off offset:64
	s_nop 0
	global_load_dwordx4 v[12:15], v[12:13], off offset:64
	s_nop 0
	global_load_dwordx4 v[16:19], v[16:17], off offset:64
	s_nop 0
	global_load_dwordx4 v[20:23], v[70:71], off offset:64
	s_nop 0
	global_load_dwordx4 v[24:27], v[24:25], off offset:64
	v_accvgpr_mov_b32 a193, a192
	v_accvgpr_mov_b32 a194, a192
	v_accvgpr_mov_b32 a195, a192
	v_accvgpr_mov_b32 a196, a192
	v_accvgpr_mov_b32 a197, a192
	v_accvgpr_mov_b32 a198, a192
	v_accvgpr_mov_b32 a199, a192
	v_accvgpr_mov_b32 a200, a192
	v_accvgpr_mov_b32 a201, a192
	v_accvgpr_mov_b32 a202, a192
	v_accvgpr_mov_b32 a203, a192
	v_accvgpr_mov_b32 a204, a192
	v_accvgpr_mov_b32 a205, a192
	v_accvgpr_mov_b32 a206, a192
	v_accvgpr_mov_b32 a207, a192


	s_waitcnt vmcnt(11)
	ds_write_b128 v84, v[0:3] offset:0
	s_waitcnt vmcnt(10)
	ds_write_b128 v84, v[28:31] offset:0x1000
	s_waitcnt vmcnt(9)
	ds_write_b128 v84, v[32:35] offset:0x2000
	s_mov_b64 s[8:9], 0xb0000
	s_mov_b64 s[6:7], 0x58000
	v_lshl_add_u64 v[74:75], v[68:69], 0, s[8:9]
	s_mov_b64 s[8:9], 0x108000
	v_mov_b32_e32 v0, 0
	s_waitcnt vmcnt(8)
	ds_write_b128 v84, v[36:39] offset:0x3000
	s_waitcnt vmcnt(7)
	ds_write_b128 v84, v[40:43] offset:0x4000
	s_waitcnt vmcnt(6)
	ds_write_b128 v84, v[44:47] offset:0x5000
	s_waitcnt lgkmcnt(0)
	v_lshl_add_u64 v[72:73], v[68:69], 0, s[6:7]
	s_mov_b32 s4, 0
	v_lshl_add_u64 v[76:77], v[68:69], 0, s[8:9]
	v_lshl_add_u64 v[78:79], v[70:71], 0, s[6:7]
	s_mov_b32 s3, -2
	v_mov_b32_e32 v1, v0
	v_mov_b32_e32 v2, v0
	v_mov_b32_e32 v3, v0
	v_mov_b32_e32 v28, v0
	v_mov_b32_e32 v29, v0
	v_mov_b32_e32 v30, v0
	v_mov_b32_e32 v31, v0
	v_mov_b32_e32 v32, v0
	v_mov_b32_e32 v33, v0
	v_mov_b32_e32 v34, v0
	v_mov_b32_e32 v35, v0
	v_mov_b32_e32 v36, v0
	v_mov_b32_e32 v37, v0
	v_mov_b32_e32 v38, v0
	v_mov_b32_e32 v39, v0
	s_barrier

.LBB0_161:
	s_abs_i32 s2, s0
	v_readlane_b32 s3, v254, 44
	s_mul_hi_u32 s3, s2, s3
	v_readlane_b32 s6, v254, 43
	s_mul_i32 s4, s3, s6
	s_sub_i32 s2, s2, s4
	s_ashr_i32 s1, s0, 31
	s_add_i32 s4, s3, 1
	s_sub_i32 s5, s2, s6
	s_cmp_ge_u32 s2, s6
	s_cselect_b32 s3, s4, s3
	s_cselect_b32 s2, s5, s2
	s_add_i32 s4, s3, 1
	s_cmp_ge_u32 s2, s6
	s_cselect_b32 s2, s4, s3
	s_xor_b32 s2, s2, s1
	s_sub_i32 s1, s2, s1
	s_lshr_b32 s2, s0, 31
	s_add_i32 s2, s0, s2
	s_ashr_i32 s3, s2, 1
	s_abs_i32 s3, s3
	v_readlane_b32 s5, v254, 46
	s_mul_hi_u32 s5, s3, s5
	v_readlane_b32 s6, v254, 45
	s_mul_i32 s5, s5, s6
	s_and_b32 s4, s2, 0xfffffe
	s_sub_i32 s3, s3, s5
	s_sub_i32 s4, s0, s4
	s_ashr_i32 s2, s2, 31
	s_sub_i32 s5, s3, s6
	s_cmp_ge_u32 s3, s6
	s_cselect_b32 s3, s5, s3
	s_sub_i32 s5, s3, s6
	s_cmp_ge_u32 s3, s6
	s_cselect_b32 s3, s5, s3
	s_xor_b32 s3, s3, s2
	s_sub_i32 s2, s3, s2
	v_readlane_b32 s3, v254, 39
	s_add_i32 s2, s3, s2
	s_lshl_b32 s1, s1, 9
	s_lshl_b32 s3, s4, 8
	v_mov_b32_e32 v160, v208
	s_add_i32 s1, s1, s3
	v_readlane_b32 s4, v253, 30
	v_ashrrev_i32_e32 v4, 2, v160
	v_add_u32_e32 v0, s1, v4
	v_ashrrev_i32_e32 v1, 31, v0
	v_lshlrev_b64 v[0:1], 11, v[0:1]
	v_readlane_b32 s5, v253, 31
	v_lshlrev_b32_e32 v5, 4, v160
	s_mulk_i32 s2, 0xc0
	v_lshl_add_u64 v[0:1], s[4:5], 0, v[0:1]
	v_and_b32_e32 v192, 48, v5
	v_lshl_add_u64 v[96:97], v[0:1], 0, v[192:193]
	v_add_u32_e32 v0, s2, v4
	v_ashrrev_i32_e32 v1, 31, v0
	v_readlane_b32 s4, v253, 16
	s_mov_b32 s3, 0x20000
	v_lshlrev_b64 v[0:1], 11, v[0:1]
	v_readlane_b32 s5, v253, 17
	v_add_co_u32_e32 v8, vcc, s3, v96
	s_nop 0
	v_lshl_add_u64 v[0:1], s[4:5], 0, v[0:1]
	v_addc_co_u32_e32 v9, vcc, 0, v97, vcc
	s_mov_b32 s4, 0x40000
	v_add_co_u32_e32 v12, vcc, s4, v96
	v_lshl_add_u64 v[98:99], v[0:1], 0, v[192:193]
	s_nop 0
	v_addc_co_u32_e32 v13, vcc, 0, v97, vcc
	v_add_co_u32_e32 v16, vcc, s75, v96
	v_bfe_u32 v6, v160, 5, 1
	s_nop 0
	v_addc_co_u32_e32 v17, vcc, 0, v97, vcc
	v_lshrrev_b32_e32 v7, 2, v160
	v_bfe_u32 v10, v160, 2, 2
	v_add_co_u32_e32 v24, vcc, s3, v98
	v_lshlrev_b32_e32 v11, 1, v160
	v_bitop3_b32 v7, v6, v7, 3 bitop3:0x78
	v_bitop3_b32 v6, v6, v10, 2 bitop3:0x36
	v_and_b32_e32 v10, 0xffffffe0, v4
	v_addc_co_u32_e32 v25, vcc, 0, v99, vcc
	v_and_b32_e32 v161, 31, v160
	v_and_b32_e32 v162, 0x80, v11
	v_lshl_add_u32 v163, v10, 1, v10
	v_add_co_u32_e32 v28, vcc, s4, v98
	v_or_b32_e32 v11, v162, v161
	v_or_b32_e32 v10, v163, v161
	global_load_dwordx4 v[0:3], v[96:97], off
	global_load_dwordx4 v[32:35], v[8:9], off
	global_load_dwordx4 v[36:39], v[12:13], off
	global_load_dwordx4 v[40:43], v[16:17], off
	global_load_dwordx4 v[44:47], v[98:99], off
	v_addc_co_u32_e32 v29, vcc, 0, v99, vcc
	v_bitop3_b32 v5, v5, 48, v160 bitop3:0x48
	v_lshlrev_b32_e32 v11, 6, v11
	v_lshlrev_b32_e32 v7, 4, v7
	v_lshlrev_b32_e32 v6, 4, v6
	v_lshl_add_u32 v10, v10, 6, v214
	global_load_dwordx4 v[48:51], v[24:25], off
	global_load_dwordx4 v[52:55], v[28:29], off
	v_or_b32_e32 v110, v11, v7
	v_or_b32_e32 v111, v11, v6
	v_or_b32_e32 v116, v10, v7
	v_or_b32_e32 v117, v10, v6
	v_lshl_or_b32 v118, v4, 6, v5
	global_load_dwordx4 v[4:7], v[96:97], off offset:64
	s_nop 0
	global_load_dwordx4 v[8:11], v[8:9], off offset:64
	s_nop 0
	global_load_dwordx4 v[12:15], v[12:13], off offset:64
	s_nop 0
	global_load_dwordx4 v[16:19], v[16:17], off offset:64
	s_nop 0
	global_load_dwordx4 v[20:23], v[98:99], off offset:64
	s_nop 0
	global_load_dwordx4 v[24:27], v[24:25], off offset:64
	s_nop 0
	global_load_dwordx4 v[28:31], v[28:29], off offset:64
	v_accvgpr_mov_b32 a193, a192
	v_accvgpr_mov_b32 a194, a192
	v_accvgpr_mov_b32 a195, a192
	v_accvgpr_mov_b32 a196, a192
	v_accvgpr_mov_b32 a197, a192
	v_accvgpr_mov_b32 a198, a192
	v_accvgpr_mov_b32 a199, a192
	v_accvgpr_mov_b32 a200, a192
	v_accvgpr_mov_b32 a201, a192
	v_accvgpr_mov_b32 a202, a192
	v_accvgpr_mov_b32 a203, a192
	v_accvgpr_mov_b32 a204, a192
	v_accvgpr_mov_b32 a205, a192
	v_accvgpr_mov_b32 a206, a192
	v_accvgpr_mov_b32 a207, a192


	s_waitcnt vmcnt(13)
	ds_write_b128 v118, v[0:3] offset:0
	s_waitcnt vmcnt(12)
	ds_write_b128 v118, v[32:35] offset:0x1000
	s_waitcnt vmcnt(11)
	ds_write_b128 v118, v[36:39] offset:0x2000
	s_mov_b64 s[8:9], 0x20000
	s_mov_b64 s[6:7], 0x40000
	s_mov_b64 s[10:11], 0x60000
	s_waitcnt vmcnt(10)
	ds_write_b128 v118, v[40:43] offset:0x3000
	s_waitcnt vmcnt(9)
	ds_write_b128 v118, v[44:47] offset:0x4000
	s_waitcnt vmcnt(8)
	ds_write_b128 v118, v[48:51] offset:0x5000
	s_waitcnt vmcnt(7)
	ds_write_b128 v118, v[52:55] offset:0x6000
	s_waitcnt lgkmcnt(0)
	v_mov_b32_e32 v0, 0
	v_lshl_add_u64 v[100:101], v[96:97], 0, s[8:9]
	s_mov_b32 s4, 0
	v_lshl_add_u64 v[102:103], v[96:97], 0, s[6:7]
	v_lshl_add_u64 v[104:105], v[96:97], 0, s[10:11]
	v_lshl_add_u64 v[106:107], v[98:99], 0, s[8:9]
	v_lshl_add_u64 v[108:109], v[98:99], 0, s[6:7]
	s_mov_b32 s3, -2
	v_mov_b32_e32 v1, v0
	v_mov_b32_e32 v2, v0
	v_mov_b32_e32 v3, v0
	v_mov_b32_e32 v128, v0
	v_mov_b32_e32 v129, v0
	v_mov_b32_e32 v130, v0
	v_mov_b32_e32 v131, v0
	v_mov_b32_e32 v32, v0
	v_mov_b32_e32 v33, v0
	v_mov_b32_e32 v34, v0
	v_mov_b32_e32 v35, v0
	s_barrier

.LBB0_223:
	s_abs_i32 s2, s0
	v_readlane_b32 s3, v254, 58
	s_mul_hi_u32 s3, s2, s3
	s_mul_i32 s4, s3, s6
	s_sub_i32 s2, s2, s4
	s_ashr_i32 s1, s0, 31
	s_add_i32 s4, s3, 1
	s_sub_i32 s5, s2, s6
	s_cmp_ge_u32 s2, s6
	s_cselect_b32 s3, s4, s3
	s_cselect_b32 s2, s5, s2
	s_add_i32 s4, s3, 1
	s_cmp_ge_u32 s2, s6
	s_cselect_b32 s2, s4, s3
	s_xor_b32 s2, s2, s1
	s_sub_i32 s2, s2, s1
	s_lshr_b32 s1, s1, 30
	s_add_i32 s1, s0, s1
	s_ashr_i32 s3, s1, 2
	s_abs_i32 s3, s3
	v_readlane_b32 s5, v254, 60
	s_mul_hi_u32 s5, s3, s5
	v_readlane_b32 s6, v254, 59
	s_mul_i32 s5, s5, s6
	s_and_b32 s4, s1, 0xfffffc
	s_sub_i32 s3, s3, s5
	s_sub_i32 s4, s0, s4
	s_ashr_i32 s1, s1, 31
	s_sub_i32 s5, s3, s6
	s_cmp_ge_u32 s3, s6
	s_cselect_b32 s3, s5, s3
	s_sub_i32 s5, s3, s6
	s_cmp_ge_u32 s3, s6
	s_cselect_b32 s3, s5, s3
	s_xor_b32 s3, s3, s1
	s_sub_i32 s1, s3, s1
	v_readlane_b32 s3, v254, 54
	s_add_i32 s3, s3, s1
	s_lshl_b32 s1, s2, 10
	s_lshl_b32 s2, s4, 8
	v_mov_b32_e32 v136, v208
	s_add_i32 s1, s1, s2
	v_readlane_b32 s4, v253, 34
	v_ashrrev_i32_e32 v4, 2, v136
	v_add_u32_e32 v0, s1, v4
	v_ashrrev_i32_e32 v1, 31, v0
	s_lshl_b32 s2, s3, 7
	v_lshlrev_b64 v[0:1], 11, v[0:1]
	v_readlane_b32 s5, v253, 35
	v_lshlrev_b32_e32 v5, 4, v136
	s_addk_i32 s2, 0x3000
	v_lshl_add_u64 v[0:1], s[4:5], 0, v[0:1]
	v_and_b32_e32 v192, 48, v5
	v_lshl_add_u64 v[68:69], v[0:1], 0, v[192:193]
	v_add_u32_e32 v0, s2, v4
	v_ashrrev_i32_e32 v1, 31, v0
	v_readlane_b32 s4, v253, 61
	s_mov_b32 s3, 0x20000
	v_lshlrev_b64 v[0:1], 11, v[0:1]
	v_readlane_b32 s5, v253, 62
	v_add_co_u32_e32 v8, vcc, s3, v68
	s_nop 0
	v_lshl_add_u64 v[0:1], s[4:5], 0, v[0:1]
	v_addc_co_u32_e32 v9, vcc, 0, v69, vcc
	s_mov_b32 s4, 0x40000
	v_add_co_u32_e32 v12, vcc, s4, v68
	v_bfe_u32 v6, v136, 5, 1
	s_nop 0
	v_addc_co_u32_e32 v13, vcc, 0, v69, vcc
	v_lshrrev_b32_e32 v7, 2, v136
	v_bfe_u32 v10, v136, 2, 2
	v_add_co_u32_e32 v16, vcc, s75, v68
	v_lshlrev_b32_e32 v11, 1, v136
	v_bitop3_b32 v7, v6, v7, 3 bitop3:0x78
	v_bitop3_b32 v6, v6, v10, 2 bitop3:0x36
	v_ashrrev_i32_e32 v10, 1, v136
	v_lshl_add_u64 v[70:71], v[0:1], 0, v[192:193]
	v_addc_co_u32_e32 v17, vcc, 0, v69, vcc
	v_and_b32_e32 v137, 31, v136
	v_and_b32_e32 v138, 0x80, v11
	v_and_b32_e32 v139, 0xffffffc0, v10
	v_add_co_u32_e32 v24, vcc, s3, v70
	v_or_b32_e32 v11, v138, v137
	v_or_b32_e32 v10, v139, v137
	global_load_dwordx4 v[0:3], v[68:69], off
	global_load_dwordx4 v[28:31], v[8:9], off
	global_load_dwordx4 v[32:35], v[12:13], off
	global_load_dwordx4 v[36:39], v[16:17], off
	global_load_dwordx4 v[40:43], v[70:71], off
	v_addc_co_u32_e32 v25, vcc, 0, v71, vcc
	v_bitop3_b32 v5, v5, 48, v136 bitop3:0x48
	v_lshlrev_b32_e32 v11, 6, v11
	v_lshlrev_b32_e32 v7, 4, v7
	v_lshlrev_b32_e32 v6, 4, v6
	v_lshl_add_u32 v10, v10, 6, v214
	global_load_dwordx4 v[44:47], v[24:25], off
	v_or_b32_e32 v80, v11, v7
	v_or_b32_e32 v81, v11, v6
	v_or_b32_e32 v82, v10, v7
	v_or_b32_e32 v83, v10, v6
	v_lshl_or_b32 v84, v4, 6, v5
	global_load_dwordx4 v[4:7], v[68:69], off offset:64
	s_nop 0
	global_load_dwordx4 v[8:11], v[8:9], off offset:64
	s_nop 0
	global_load_dwordx4 v[12:15], v[12:13], off offset:64
	s_nop 0
	global_load_dwordx4 v[16:19], v[16:17], off offset:64
	s_nop 0
	global_load_dwordx4 v[20:23], v[70:71], off offset:64
	s_nop 0
	global_load_dwordx4 v[24:27], v[24:25], off offset:64
	v_accvgpr_mov_b32 a193, a192
	v_accvgpr_mov_b32 a194, a192
	v_accvgpr_mov_b32 a195, a192
	v_accvgpr_mov_b32 a196, a192
	v_accvgpr_mov_b32 a197, a192
	v_accvgpr_mov_b32 a198, a192
	v_accvgpr_mov_b32 a199, a192
	v_accvgpr_mov_b32 a200, a192
	v_accvgpr_mov_b32 a201, a192
	v_accvgpr_mov_b32 a202, a192
	v_accvgpr_mov_b32 a203, a192
	v_accvgpr_mov_b32 a204, a192
	v_accvgpr_mov_b32 a205, a192
	v_accvgpr_mov_b32 a206, a192
	v_accvgpr_mov_b32 a207, a192


	s_waitcnt vmcnt(11)
	ds_write_b128 v84, v[0:3] offset:0
	s_waitcnt vmcnt(10)
	ds_write_b128 v84, v[28:31] offset:0x1000
	s_waitcnt vmcnt(9)
	ds_write_b128 v84, v[32:35] offset:0x2000
	s_mov_b64 s[6:7], 0x40000
	s_mov_b64 s[8:9], 0x20000
	v_lshl_add_u64 v[74:75], v[68:69], 0, s[6:7]
	s_mov_b64 s[6:7], 0x60000
	v_mov_b32_e32 v0, 0
	s_waitcnt vmcnt(8)
	ds_write_b128 v84, v[36:39] offset:0x3000
	s_waitcnt vmcnt(7)
	ds_write_b128 v84, v[40:43] offset:0x4000
	s_waitcnt vmcnt(6)
	ds_write_b128 v84, v[44:47] offset:0x5000
	s_waitcnt lgkmcnt(0)
	v_lshl_add_u64 v[72:73], v[68:69], 0, s[8:9]
	s_mov_b32 s4, 0
	v_lshl_add_u64 v[76:77], v[68:69], 0, s[6:7]
	v_lshl_add_u64 v[78:79], v[70:71], 0, s[8:9]
	s_mov_b32 s3, -2
	v_mov_b32_e32 v1, v0
	v_mov_b32_e32 v2, v0
	v_mov_b32_e32 v3, v0
	v_mov_b32_e32 v28, v0
	v_mov_b32_e32 v29, v0
	v_mov_b32_e32 v30, v0
	v_mov_b32_e32 v31, v0
	v_mov_b32_e32 v32, v0
	v_mov_b32_e32 v33, v0
	v_mov_b32_e32 v34, v0
	v_mov_b32_e32 v35, v0
	v_mov_b32_e32 v36, v0
	v_mov_b32_e32 v37, v0
	v_mov_b32_e32 v38, v0
	v_mov_b32_e32 v39, v0
	s_barrier

.LBB0_772:
	s_abs_i32 s1, s20
	v_readlane_b32 s2, v255, 3
	s_mul_hi_u32 s2, s1, s2
	s_mul_i32 s3, s2, s5
	s_sub_i32 s1, s1, s3
	s_ashr_i32 s0, s20, 31
	s_add_i32 s3, s2, 1
	s_sub_i32 s4, s1, s5
	s_cmp_ge_u32 s1, s5
	s_cselect_b32 s2, s3, s2
	s_cselect_b32 s1, s4, s1
	s_add_i32 s3, s2, 1
	s_cmp_ge_u32 s1, s5
	s_cselect_b32 s1, s3, s2
	s_xor_b32 s1, s1, s0
	s_sub_i32 s0, s1, s0
	s_mul_hi_i32 s1, s20, 0x92492493
	s_add_i32 s1, s1, s20
	s_lshr_b32 s2, s1, 31
	s_ashr_i32 s1, s1, 2
	s_add_i32 s1, s1, s2
	s_mul_i32 s2, s1, 7
	s_mul_i32 s0, s0, 7
	s_sub_i32 s2, s20, s2
	s_add_i32 s0, s0, s2
	s_ashr_i32 s2, s1, 31
	s_abs_i32 s1, s1
	v_readlane_b32 s3, v255, 5
	s_mul_hi_u32 s3, s1, s3
	v_readlane_b32 s4, v255, 4
	s_mul_i32 s3, s3, s4
	s_sub_i32 s1, s1, s3
	s_sub_i32 s3, s1, s4
	s_cmp_ge_u32 s1, s4
	s_cselect_b32 s1, s3, s1
	s_sub_i32 s3, s1, s4
	s_cmp_ge_u32 s1, s4
	v_mov_b32_e32 v4, v208
	s_cselect_b32 s1, s3, s1
	s_lshl_b32 s0, s0, 8
	s_xor_b32 s1, s1, s2
	v_ashrrev_i32_e32 v5, 2, v4
	v_add_u32_e32 v0, s0, v5
	s_sub_i32 s1, s1, s2
	v_readlane_b32 s2, v254, 62
	v_ashrrev_i32_e32 v1, 31, v0
	s_add_i32 s1, s2, s1
	v_lshlrev_b64 v[0:1], 11, v[0:1]
	v_lshlrev_b32_e32 v6, 4, v4
	s_lshl_b32 s1, s1, 7
	v_lshl_add_u64 v[0:1], s[90:91], 0, v[0:1]
	v_and_b32_e32 v192, 48, v6
	v_lshl_add_u64 v[64:65], v[0:1], 0, v[192:193]
	v_add_u32_e32 v0, s1, v5
	v_ashrrev_i32_e32 v1, 31, v0
	v_readlane_b32 s2, v253, 16
	v_lshlrev_b64 v[0:1], 11, v[0:1]
	v_readlane_b32 s3, v253, 17
	v_bitop3_b32 v6, v6, 48, v4 bitop3:0x48
	v_and_b32_e32 v207, 31, v4
	v_lshl_add_u64 v[0:1], s[2:3], 0, v[0:1]
	s_mov_b32 s2, 0x20000
	v_add_co_u32_e32 v8, vcc, s2, v64
	s_mov_b32 s3, 0x40000
	s_nop 0
	v_addc_co_u32_e32 v9, vcc, 0, v65, vcc
	v_add_co_u32_e32 v12, vcc, s3, v64
	v_lshrrev_b32_e32 v7, 5, v4
	s_nop 0
	v_addc_co_u32_e32 v13, vcc, 0, v65, vcc
	v_add_co_u32_e32 v16, vcc, s75, v64
	v_bfe_u32 v239, v4, 5, 1
	v_bfe_u32 v10, v4, 2, 2
	v_lshlrev_b32_e32 v11, 1, v4
	v_ashrrev_i32_e32 v4, 1, v4
	v_lshl_add_u64 v[66:67], v[0:1], 0, v[192:193]
	v_addc_co_u32_e32 v17, vcc, 0, v65, vcc
	v_and_b32_e32 v192, 0x80, v11
	v_and_b32_e32 v242, 0xffffffc0, v4
	v_add_co_u32_e32 v24, vcc, s2, v66
	v_or_b32_e32 v11, v192, v207
	v_bitop3_b32 v7, v7, v10, 1 bitop3:0x6c
	v_bitop3_b32 v10, v239, v10, 2 bitop3:0x36
	v_or_b32_e32 v4, v242, v207
	global_load_dwordx4 v[0:3], v[64:65], off
	global_load_dwordx4 v[28:31], v[8:9], off
	global_load_dwordx4 v[32:35], v[12:13], off
	global_load_dwordx4 v[36:39], v[16:17], off
	global_load_dwordx4 v[40:43], v[66:67], off
	v_addc_co_u32_e32 v25, vcc, 0, v67, vcc
	v_lshlrev_b32_e32 v11, 6, v11
	v_lshlrev_b32_e32 v7, 4, v7
	v_lshlrev_b32_e32 v10, 4, v10
	v_lshl_add_u32 v4, v4, 6, v214
	global_load_dwordx4 v[44:47], v[24:25], off
	v_or_b32_e32 v76, v11, v7
	v_or_b32_e32 v77, v11, v10
	v_or_b32_e32 v78, v4, v7
	v_or_b32_e32 v79, v4, v10
	v_lshl_or_b32 v80, v5, 6, v6
	global_load_dwordx4 v[4:7], v[64:65], off offset:64
	s_nop 0
	global_load_dwordx4 v[8:11], v[8:9], off offset:64
	s_nop 0
	global_load_dwordx4 v[12:15], v[12:13], off offset:64
	s_nop 0
	global_load_dwordx4 v[16:19], v[16:17], off offset:64
	s_nop 0
	global_load_dwordx4 v[20:23], v[66:67], off offset:64
	s_nop 0
	global_load_dwordx4 v[24:27], v[24:25], off offset:64
	v_accvgpr_mov_b32 a193, a192
	v_accvgpr_mov_b32 a194, a192
	v_accvgpr_mov_b32 a195, a192
	v_accvgpr_mov_b32 a196, a192
	v_accvgpr_mov_b32 a197, a192
	v_accvgpr_mov_b32 a198, a192
	v_accvgpr_mov_b32 a199, a192
	v_accvgpr_mov_b32 a200, a192
	v_accvgpr_mov_b32 a201, a192
	v_accvgpr_mov_b32 a202, a192
	v_accvgpr_mov_b32 a203, a192
	v_accvgpr_mov_b32 a204, a192
	v_accvgpr_mov_b32 a205, a192
	v_accvgpr_mov_b32 a206, a192
	v_accvgpr_mov_b32 a207, a192


	s_waitcnt vmcnt(11)
	ds_write_b128 v80, v[0:3] offset:0
	s_waitcnt vmcnt(10)
	ds_write_b128 v80, v[28:31] offset:0x1000
	s_waitcnt vmcnt(9)
	ds_write_b128 v80, v[32:35] offset:0x2000
	s_mov_b64 s[4:5], 0x40000
	s_mov_b64 s[6:7], 0x20000
	v_lshl_add_u64 v[70:71], v[64:65], 0, s[4:5]
	s_mov_b64 s[4:5], 0x60000
	v_mov_b32_e32 v0, 0
	s_waitcnt vmcnt(8)
	ds_write_b128 v80, v[36:39] offset:0x3000
	s_waitcnt vmcnt(7)
	ds_write_b128 v80, v[40:43] offset:0x4000
	s_waitcnt vmcnt(6)
	ds_write_b128 v80, v[44:47] offset:0x5000
	s_waitcnt lgkmcnt(0)
	v_lshl_add_u64 v[68:69], v[64:65], 0, s[6:7]
	s_mov_b32 s3, 0
	v_lshl_add_u64 v[72:73], v[64:65], 0, s[4:5]
	v_lshl_add_u64 v[74:75], v[66:67], 0, s[6:7]
	s_mov_b32 s2, -2
	v_mov_b32_e32 v1, v0
	v_mov_b32_e32 v2, v0
	v_mov_b32_e32 v3, v0
	v_mov_b32_e32 v28, v0
	v_mov_b32_e32 v29, v0
	v_mov_b32_e32 v30, v0
	v_mov_b32_e32 v31, v0
	v_mov_b32_e32 v32, v0
	v_mov_b32_e32 v33, v0
	v_mov_b32_e32 v34, v0
	v_mov_b32_e32 v35, v0
	v_mov_b32_e32 v36, v0
	v_mov_b32_e32 v37, v0
	v_mov_b32_e32 v38, v0
	v_mov_b32_e32 v39, v0
	s_barrier
